# gated-norm phase: 16-lane sum of squares by four DPP row_ror adds instead of four ds_bpermute round trips
# speedup vs baseline: 1.0005x; 1.0005x over previous
.LBB0_796:
	v_add_u32_e32 v46, s20, v38
	v_cmp_gt_i32_e64 s[6:7], s52, v46
	v_add_u32_e32 v45, s23, v38
	v_cmp_gt_i32_e64 s[4:5], s52, v45
	v_cndmask_b32_e64 v12, v38, v46, s[6:7]
	v_ashrrev_i32_e32 v8, 2, v12
	v_ashrrev_i32_e32 v9, 31, v8
	v_add_u32_e32 v44, s24, v38
	v_lshlrev_b64 v[10:11], 11, v[8:9]
	v_lshlrev_b32_e32 v12, 8, v12
	v_lshlrev_b64 v[8:9], 10, v[8:9]
	v_cndmask_b32_e64 v16, v38, v45, s[4:5]
	v_cmp_gt_i32_e32 vcc, s52, v44
	v_lshl_add_u64 v[10:11], s[12:13], 0, v[10:11]
	v_and_b32_e32 v192, 0x300, v12
	v_lshl_add_u64 v[8:9], s[14:15], 0, v[8:9]
	v_ashrrev_i32_e32 v12, 2, v16
	v_lshlrev_b32_e32 v16, 8, v16
	v_cndmask_b32_e32 v21, v38, v44, vcc
	v_lshl_add_u64 v[10:11], v[10:11], 0, v[192:193]
	v_lshl_add_u64 v[8:9], v[8:9], 0, v[192:193]
	v_ashrrev_i32_e32 v13, 31, v12
	v_and_b32_e32 v192, 0x300, v16
	v_ashrrev_i32_e32 v16, 2, v21
	v_lshlrev_b64 v[14:15], 11, v[12:13]
	v_lshlrev_b64 v[12:13], 10, v[12:13]
	v_ashrrev_i32_e32 v17, 31, v16
	v_lshl_add_u64 v[14:15], s[12:13], 0, v[14:15]
	v_lshl_add_u64 v[12:13], s[14:15], 0, v[12:13]
	v_lshlrev_b64 v[18:19], 11, v[16:17]
	v_lshlrev_b32_e32 v21, 8, v21
	v_lshlrev_b64 v[16:17], 10, v[16:17]
	v_lshl_add_u64 v[14:15], v[14:15], 0, v[192:193]
	v_lshl_add_u64 v[12:13], v[12:13], 0, v[192:193]
	v_and_b32_e32 v192, 0x300, v21
	v_lshl_add_u64 v[16:17], s[14:15], 0, v[16:17]
	v_lshl_add_u64 v[56:57], v[16:17], 0, v[192:193]
	v_ashrrev_i32_e32 v16, 2, v38
	v_ashrrev_i32_e32 v17, 31, v16
	v_and_b32_e32 v20, 0x180, v43
	v_lshl_add_u64 v[18:19], s[12:13], 0, v[18:19]
	v_lshlrev_b64 v[58:59], 11, v[16:17]
	v_lshl_add_u64 v[36:37], v[18:19], 0, v[192:193]
	v_lshlrev_b32_e32 v192, 1, v20
	v_lshlrev_b64 v[18:19], 10, v[16:17]
	v_lshl_add_u64 v[16:17], s[12:13], 0, v[58:59]
	v_mov_b32_e32 v35, v193
	v_lshl_add_u64 v[18:19], s[14:15], 0, v[18:19]
	v_lshl_add_u64 v[16:17], v[16:17], 0, v[192:193]
	v_lshl_add_u64 v[18:19], v[18:19], 0, v[192:193]
	v_lshl_add_u64 v[16:17], v[16:17], 0, v[34:35]
	global_load_dwordx4 v[48:51], v[16:17], off
	v_lshl_add_u64 v[16:17], v[18:19], 0, v[34:35]
	global_load_dwordx4 v[52:55], v[16:17], off
	v_lshl_add_u64 v[10:11], v[10:11], 0, v[34:35]
	v_lshl_add_u64 v[8:9], v[8:9], 0, v[34:35]
	global_load_dwordx4 v[28:31], v[10:11], off
	global_load_dwordx4 v[24:27], v[8:9], off
	v_lshl_add_u64 v[8:9], v[14:15], 0, v[34:35]
	v_lshl_add_u64 v[10:11], v[12:13], 0, v[34:35]
	global_load_dwordx4 v[20:23], v[8:9], off
	global_load_dwordx4 v[16:19], v[10:11], off
	v_lshl_add_u64 v[8:9], v[36:37], 0, v[34:35]
	v_lshl_add_u64 v[10:11], v[56:57], 0, v[34:35]
	global_load_dwordx4 v[12:15], v[8:9], off
	s_nop 0
	global_load_dwordx4 v[8:11], v[10:11], off
	v_lshl_add_u64 v[36:37], v[32:33], 0, v[192:193]
	s_waitcnt vmcnt(0)
	v_lshlrev_b32_e32 v62, 16, v50
	v_and_b32_e32 v63, 0xffff0000, v50
	v_lshlrev_b32_e32 v50, 16, v54
	v_lshlrev_b32_e32 v66, 16, v48
	v_mul_f32_e32 v35, 0xbfb8aa3b, v50
	v_lshlrev_b32_e32 v56, 16, v51
	v_and_b32_e32 v57, 0xffff0000, v51
	v_lshlrev_b32_e32 v60, 16, v55
	v_and_b32_e32 v61, 0xffff0000, v55
	v_and_b32_e32 v51, 0xffff0000, v54
	v_lshlrev_b32_e32 v54, 16, v49
	v_and_b32_e32 v55, 0xffff0000, v49
	v_and_b32_e32 v67, 0xffff0000, v48
	v_mul_f32_e32 v72, v66, v66
	v_exp_f32_e32 v35, v35
	v_pk_mul_f32 v[70:71], v[54:55], v[54:55]
	v_fmac_f32_e32 v72, v67, v67
	v_mul_f32_e32 v47, 0xbfb8aa3b, v51
	v_add_f32_e32 v70, v72, v70
	v_pk_mul_f32 v[68:69], v[62:63], v[62:63]
	v_exp_f32_e32 v47, v47
	v_add_f32_e32 v70, v70, v71
	v_add_f32_e32 v68, v70, v68
	v_add_f32_e32 v35, 1.0, v35
	v_pk_mul_f32 v[48:49], v[56:57], v[56:57]
	v_rcp_f32_e32 v70, v35
	v_add_f32_e32 v35, v68, v69
	v_add_f32_e32 v35, v35, v48
	v_add_f32_e32 v47, 1.0, v47
	v_add_f32_e32 v35, v35, v49
	v_rcp_f32_e32 v71, v47
	v_lshlrev_b32_e32 v64, 16, v53
	v_and_b32_e32 v65, 0xffff0000, v53
	v_mul_f32_e32 v53, 0xbfb8aa3b, v64
	v_mul_f32_e32 v49, 0xbfb8aa3b, v65
	s_nop 1
	v_add_f32_dpp v35, v35, v35 row_ror:1 row_mask:0xf bank_mask:0xf
	v_exp_f32_e32 v53, v53
	v_exp_f32_e32 v49, v49
	v_lshlrev_b32_e32 v68, 16, v52
	v_and_b32_e32 v69, 0xffff0000, v52
	s_nop 1
	v_add_f32_dpp v35, v35, v35 row_ror:2 row_mask:0xf bank_mask:0xf
	v_add_f32_e32 v48, 1.0, v53
	v_add_f32_e32 v49, 1.0, v49
	v_rcp_f32_e32 v48, v48
	v_rcp_f32_e32 v49, v49
	s_nop 1
	v_add_f32_dpp v35, v35, v35 row_ror:4 row_mask:0xf bank_mask:0xf
	v_mul_f32_e32 v52, 0xbfb8aa3b, v68
	v_pk_mul_f32 v[48:49], v[48:49], v[64:65]
	v_mul_f32_e32 v53, 0xbfb8aa3b, v69
	v_exp_f32_e32 v52, v52
	s_nop 1
	v_add_f32_dpp v35, v35, v35 row_ror:8 row_mask:0xf bank_mask:0xf
	v_fmamk_f32 v35, v35, 0x3c000000, v238
	v_mul_f32_e32 v47, 0x4b800000, v35
	v_cmp_gt_f32_e64 s[8:9], s66, v35
	v_exp_f32_e32 v53, v53
	v_add_f32_e32 v52, 1.0, v52
	v_cndmask_b32_e64 v35, v35, v47, s[8:9]
	v_rsq_f32_e32 v35, v35
	v_add_f32_e32 v53, 1.0, v53
	v_rcp_f32_e32 v52, v52
	v_rcp_f32_e32 v53, v53
	v_mul_f32_e32 v47, 0x45800000, v35
	v_cndmask_b32_e64 v64, v35, v47, s[8:9]
	v_mul_f32_e32 v35, 0xbfb8aa3b, v60
	v_exp_f32_e32 v35, v35
	v_mul_f32_e32 v47, 0xbfb8aa3b, v61
	v_exp_f32_e32 v47, v47
	v_pk_mul_f32 v[54:55], v[64:65], v[54:55] op_sel_hi:[0,1]
	v_pk_mul_f32 v[54:55], v[2:3], v[54:55]
	v_add_f32_e32 v35, 1.0, v35
	v_pk_mul_f32 v[54:55], v[54:55], v[48:49]
	v_pk_mul_f32 v[48:49], v[64:65], v[62:63] op_sel_hi:[0,1]
	v_rcp_f32_e32 v62, v35
	v_add_f32_e32 v35, 1.0, v47
	v_rcp_f32_e32 v63, v35
	v_pk_mul_f32 v[50:51], v[70:71], v[50:51]
	v_pk_mul_f32 v[48:49], v[4:5], v[48:49]
	v_pk_mul_f32 v[66:67], v[64:65], v[66:67] op_sel_hi:[0,1]
	v_pk_mul_f32 v[50:51], v[48:49], v[50:51]
	v_pk_mul_f32 v[48:49], v[64:65], v[56:57] op_sel_hi:[0,1]
	v_pk_mul_f32 v[52:53], v[52:53], v[68:69]
	v_pk_mul_f32 v[66:67], v[0:1], v[66:67]
	v_pk_mul_f32 v[48:49], v[6:7], v[48:49]
	v_pk_mul_f32 v[56:57], v[62:63], v[60:61]
	v_pk_mul_f32 v[52:53], v[66:67], v[52:53]
	v_pk_mul_f32 v[56:57], v[48:49], v[56:57]
	v_cvt_pk_bf16_f32 v48, v52, v53
	v_cvt_pk_bf16_f32 v49, v54, v55
	v_cvt_pk_bf16_f32 v50, v50, v51
	v_cvt_pk_bf16_f32 v51, v56, v57
	v_lshl_add_u64 v[52:53], v[36:37], 0, v[58:59]
	global_store_dwordx4 v[52:53], v[48:51], off
	s_and_saveexec_b64 s[8:9], s[6:7]
	s_cbranch_execnz .LBB0_799
	s_or_b64 exec, exec, s[8:9]
	s_and_saveexec_b64 s[6:7], s[4:5]
	s_cbranch_execnz .LBB0_800

.LBB0_799:
	v_lshlrev_b32_e32 v64, 16, v28
	v_lshlrev_b32_e32 v54, 16, v30
	v_and_b32_e32 v55, 0xffff0000, v30
	v_lshlrev_b32_e32 v30, 16, v26
	v_lshlrev_b32_e32 v58, 16, v29
	v_and_b32_e32 v59, 0xffff0000, v29
	v_and_b32_e32 v65, 0xffff0000, v28
	v_mul_f32_e32 v28, v64, v64
	v_lshlrev_b32_e32 v48, 16, v31
	v_and_b32_e32 v49, 0xffff0000, v31
	v_and_b32_e32 v31, 0xffff0000, v26
	v_mul_f32_e32 v26, 0xbfb8aa3b, v30
	v_pk_mul_f32 v[62:63], v[58:59], v[58:59]
	v_fmac_f32_e32 v28, v65, v65
	v_exp_f32_e32 v35, v26
	v_mul_f32_e32 v26, 0xbfb8aa3b, v31
	v_add_f32_e32 v28, v28, v62
	v_lshlrev_b32_e32 v50, 16, v27
	v_and_b32_e32 v51, 0xffff0000, v27
	v_exp_f32_e32 v47, v26
	v_pk_mul_f32 v[26:27], v[54:55], v[54:55]
	v_add_f32_e32 v28, v28, v63
	v_add_f32_e32 v26, v28, v26
	v_pk_mul_f32 v[52:53], v[48:49], v[48:49]
	v_add_f32_e32 v26, v26, v27
	v_lshlrev_b32_e32 v60, 16, v25
	v_add_f32_e32 v26, v26, v52
	v_and_b32_e32 v61, 0xffff0000, v25
	v_mul_f32_e32 v25, 0xbfb8aa3b, v60
	v_add_f32_e32 v27, v26, v53
	v_exp_f32_e32 v25, v25
	v_add_f32_e32 v35, 1.0, v35
	v_mul_f32_e32 v26, 0xbfb8aa3b, v61
	v_add_f32_e32 v25, 1.0, v25
	v_rcp_f32_e32 v56, v35
	v_add_f32_e32 v35, 1.0, v47
	v_exp_f32_e32 v29, v26
	v_rcp_f32_e32 v26, v25
	s_nop 1
	v_add_f32_dpp v25, v27, v27 row_ror:1 row_mask:0xf bank_mask:0xf
	v_rcp_f32_e32 v57, v35
	v_add_f32_e32 v27, 1.0, v29
	v_lshlrev_b32_e32 v28, 16, v24
	v_and_b32_e32 v29, 0xffff0000, v24
	v_mul_f32_e32 v47, 0xbfb8aa3b, v29
	s_nop 1
	v_add_f32_dpp v24, v25, v25 row_ror:2 row_mask:0xf bank_mask:0xf
	v_mul_f32_e32 v35, 0xbfb8aa3b, v28
	v_exp_f32_e32 v35, v35
	v_exp_f32_e32 v47, v47
	v_rcp_f32_e32 v27, v27
	s_nop 1
	v_add_f32_dpp v52, v24, v24 row_ror:4 row_mask:0xf bank_mask:0xf
	v_add_f32_e32 v24, 1.0, v35
	v_add_f32_e32 v25, 1.0, v47
	v_rcp_f32_e32 v24, v24
	v_rcp_f32_e32 v25, v25
	s_nop 1
	v_add_f32_dpp v35, v52, v52 row_ror:8 row_mask:0xf bank_mask:0xf
	v_fmamk_f32 v35, v35, 0x3c000000, v238
	v_mul_f32_e32 v47, 0x4b800000, v35
	v_cmp_gt_f32_e64 s[6:7], s66, v35
	v_pk_mul_f32 v[24:25], v[24:25], v[28:29]
	v_pk_mul_f32 v[26:27], v[26:27], v[60:61]
	v_cndmask_b32_e64 v35, v35, v47, s[6:7]
	v_rsq_f32_e32 v35, v35
	v_ashrrev_i32_e32 v46, 2, v46
	v_pk_mul_f32 v[30:31], v[56:57], v[30:31]
	v_ashrrev_i32_e32 v47, 31, v46
	v_mul_f32_e32 v28, 0x45800000, v35
	v_cndmask_b32_e64 v28, v35, v28, s[6:7]
	v_pk_mul_f32 v[52:53], v[28:29], v[64:65] op_sel_hi:[0,1]
	v_pk_mul_f32 v[52:53], v[0:1], v[52:53]
	v_mul_f32_e32 v35, 0xbfb8aa3b, v51
	v_pk_mul_f32 v[24:25], v[52:53], v[24:25]
	v_pk_mul_f32 v[52:53], v[28:29], v[58:59] op_sel_hi:[0,1]
	v_pk_mul_f32 v[52:53], v[2:3], v[52:53]
	v_exp_f32_e32 v35, v35
	v_pk_mul_f32 v[26:27], v[52:53], v[26:27]
	v_pk_mul_f32 v[52:53], v[28:29], v[54:55] op_sel_hi:[0,1]
	v_mul_f32_e32 v29, 0xbfb8aa3b, v50
	v_exp_f32_e32 v29, v29
	v_pk_mul_f32 v[52:53], v[4:5], v[52:53]
	v_cvt_pk_bf16_f32 v24, v24, v25
	v_pk_mul_f32 v[30:31], v[52:53], v[30:31]
	v_add_f32_e32 v29, 1.0, v29
	v_rcp_f32_e32 v54, v29
	v_add_f32_e32 v29, 1.0, v35
	v_rcp_f32_e32 v55, v29
	v_pk_mul_f32 v[28:29], v[28:29], v[48:49] op_sel_hi:[0,1]
	v_pk_mul_f32 v[28:29], v[6:7], v[28:29]
	v_cvt_pk_bf16_f32 v25, v26, v27
	v_pk_mul_f32 v[48:49], v[54:55], v[50:51]
	v_cvt_pk_bf16_f32 v26, v30, v31
	v_pk_mul_f32 v[28:29], v[28:29], v[48:49]
	s_nop 0
	v_cvt_pk_bf16_f32 v27, v28, v29
	v_lshlrev_b64 v[28:29], 11, v[46:47]
	v_lshl_add_u64 v[28:29], v[36:37], 0, v[28:29]
	global_store_dwordx4 v[28:29], v[24:27], off
	s_or_b64 exec, exec, s[8:9]
	s_and_saveexec_b64 s[6:7], s[4:5]
	s_cbranch_execz .LBB0_798
.LBB0_800:
	v_lshlrev_b32_e32 v24, 16, v20
	v_and_b32_e32 v25, 0xffff0000, v20
	v_lshlrev_b32_e32 v20, 16, v21
	v_and_b32_e32 v21, 0xffff0000, v21
	v_mul_f32_e32 v35, v24, v24
	v_pk_mul_f32 v[28:29], v[20:21], v[20:21]
	v_fmac_f32_e32 v35, v25, v25
	v_lshlrev_b32_e32 v26, 16, v22
	v_and_b32_e32 v27, 0xffff0000, v22
	v_add_f32_e32 v28, v35, v28
	v_pk_mul_f32 v[30:31], v[26:27], v[26:27]
	v_add_f32_e32 v28, v28, v29
	v_lshlrev_b32_e32 v22, 16, v23
	v_and_b32_e32 v23, 0xffff0000, v23
	v_add_f32_e32 v28, v28, v30
	v_pk_mul_f32 v[46:47], v[22:23], v[22:23]
	v_add_f32_e32 v28, v28, v31
	v_add_f32_e32 v28, v28, v46
	v_add_f32_e32 v28, v28, v47
	s_nop 1
	v_add_f32_dpp v28, v28, v28 row_ror:1 row_mask:0xf bank_mask:0xf
	s_nop 1
	v_add_f32_dpp v30, v28, v28 row_ror:2 row_mask:0xf bank_mask:0xf
	v_lshlrev_b32_e32 v28, 16, v16
	v_and_b32_e32 v29, 0xffff0000, v16
	v_mul_f32_e32 v47, 0xbfb8aa3b, v29
	v_exp_f32_e32 v47, v47
	s_nop 1
	v_add_f32_dpp v35, v30, v30 row_ror:4 row_mask:0xf bank_mask:0xf
	v_lshlrev_b32_e32 v16, 16, v17
	v_add_f32_e32 v47, 1.0, v47
	v_rcp_f32_e32 v47, v47
	v_and_b32_e32 v17, 0xffff0000, v17
	s_nop 1
	v_add_f32_dpp v35, v35, v35 row_ror:8 row_mask:0xf bank_mask:0xf
	v_fmamk_f32 v35, v35, 0x3c000000, v238
	v_mul_f32_e32 v46, 0x4b800000, v35
	v_cmp_gt_f32_e64 s[4:5], s66, v35
	v_lshlrev_b32_e32 v30, 16, v18
	v_and_b32_e32 v31, 0xffff0000, v18
	v_cndmask_b32_e64 v35, v35, v46, s[4:5]
	v_mul_f32_e32 v46, 0xbfb8aa3b, v28
	v_exp_f32_e32 v46, v46
	v_rsq_f32_e32 v35, v35
	v_lshlrev_b32_e32 v18, 16, v19
	v_and_b32_e32 v19, 0xffff0000, v19
	v_add_f32_e32 v46, 1.0, v46
	v_rcp_f32_e32 v46, v46
	v_mul_f32_e32 v48, 0x45800000, v35
	v_cndmask_b32_e64 v48, v35, v48, s[4:5]
	v_pk_mul_f32 v[24:25], v[48:49], v[24:25] op_sel_hi:[0,1]
	v_pk_mul_f32 v[24:25], v[0:1], v[24:25]
	v_pk_mul_f32 v[28:29], v[46:47], v[28:29]
	v_mul_f32_e32 v35, 0xbfb8aa3b, v16
	v_pk_mul_f32 v[24:25], v[24:25], v[28:29]
	v_mul_f32_e32 v28, 0xbfb8aa3b, v17
	v_exp_f32_e32 v35, v35
	v_exp_f32_e32 v29, v28
	v_pk_mul_f32 v[20:21], v[48:49], v[20:21] op_sel_hi:[0,1]
	v_pk_mul_f32 v[20:21], v[2:3], v[20:21]
	v_add_f32_e32 v28, 1.0, v35
	v_add_f32_e32 v29, 1.0, v29
	v_rcp_f32_e32 v28, v28
	v_rcp_f32_e32 v29, v29
	v_mul_f32_e32 v35, 0xbfb8aa3b, v30
	v_exp_f32_e32 v35, v35
	v_pk_mul_f32 v[26:27], v[48:49], v[26:27] op_sel_hi:[0,1]
	v_pk_mul_f32 v[16:17], v[28:29], v[16:17]
	v_mul_f32_e32 v28, 0xbfb8aa3b, v18
	v_pk_mul_f32 v[20:21], v[20:21], v[16:17]
	v_mul_f32_e32 v17, 0xbfb8aa3b, v31
	v_exp_f32_e32 v17, v17
	v_mul_f32_e32 v29, 0xbfb8aa3b, v19
	v_exp_f32_e32 v28, v28
	v_exp_f32_e32 v29, v29
	v_add_f32_e32 v16, 1.0, v35
	v_add_f32_e32 v17, 1.0, v17
	v_rcp_f32_e32 v16, v16
	v_rcp_f32_e32 v17, v17
	v_add_f32_e32 v28, 1.0, v28
	v_add_f32_e32 v29, 1.0, v29
	v_rcp_f32_e32 v28, v28
	v_rcp_f32_e32 v29, v29
	v_pk_mul_f32 v[26:27], v[4:5], v[26:27]
	v_pk_mul_f32 v[16:17], v[16:17], v[30:31]
	v_pk_mul_f32 v[18:19], v[28:29], v[18:19]
	v_pk_mul_f32 v[26:27], v[26:27], v[16:17]
	v_pk_mul_f32 v[16:17], v[48:49], v[22:23] op_sel_hi:[0,1]
	v_ashrrev_i32_e32 v28, 2, v45
	v_pk_mul_f32 v[16:17], v[6:7], v[16:17]
	v_ashrrev_i32_e32 v29, 31, v28
	v_pk_mul_f32 v[22:23], v[16:17], v[18:19]
	v_cvt_pk_bf16_f32 v17, v20, v21
	v_lshlrev_b64 v[20:21], 11, v[28:29]
	v_cvt_pk_bf16_f32 v16, v24, v25
	v_cvt_pk_bf16_f32 v18, v26, v27
	v_cvt_pk_bf16_f32 v19, v22, v23
	v_lshl_add_u64 v[20:21], v[36:37], 0, v[20:21]
	global_store_dwordx4 v[20:21], v[16:19], off
	s_or_b64 exec, exec, s[6:7]
	s_and_saveexec_b64 s[4:5], vcc
	s_cbranch_execz .LBB0_795
.LBB0_801:
	v_lshlrev_b32_e32 v16, 16, v12
	v_and_b32_e32 v17, 0xffff0000, v12
	v_lshlrev_b32_e32 v12, 16, v13
	v_and_b32_e32 v13, 0xffff0000, v13
	v_mul_f32_e32 v26, v16, v16
	v_pk_mul_f32 v[20:21], v[12:13], v[12:13]
	v_fmac_f32_e32 v26, v17, v17
	v_lshlrev_b32_e32 v18, 16, v14
	v_and_b32_e32 v19, 0xffff0000, v14
	v_add_f32_e32 v20, v26, v20
	v_pk_mul_f32 v[22:23], v[18:19], v[18:19]
	v_add_f32_e32 v20, v20, v21
	v_lshlrev_b32_e32 v14, 16, v15
	v_and_b32_e32 v15, 0xffff0000, v15
	v_add_f32_e32 v20, v20, v22
	v_pk_mul_f32 v[24:25], v[14:15], v[14:15]
	v_add_f32_e32 v20, v20, v23
	v_add_f32_e32 v20, v20, v24
	v_add_f32_e32 v20, v20, v25
	s_nop 1
	v_add_f32_dpp v20, v20, v20 row_ror:1 row_mask:0xf bank_mask:0xf
	s_nop 1
	v_add_f32_dpp v22, v20, v20 row_ror:2 row_mask:0xf bank_mask:0xf
	v_lshlrev_b32_e32 v20, 16, v8
	v_and_b32_e32 v21, 0xffff0000, v8
	v_lshlrev_b32_e32 v8, 16, v9
	v_and_b32_e32 v9, 0xffff0000, v9
	s_nop 1
	v_add_f32_dpp v24, v22, v22 row_ror:4 row_mask:0xf bank_mask:0xf
	v_lshlrev_b32_e32 v22, 16, v10
	v_and_b32_e32 v23, 0xffff0000, v10
	v_lshlrev_b32_e32 v10, 16, v11
	v_and_b32_e32 v11, 0xffff0000, v11
	s_nop 1
	v_add_f32_dpp v24, v24, v24 row_ror:8 row_mask:0xf bank_mask:0xf
	v_fmamk_f32 v24, v24, 0x3c000000, v238
	v_mul_f32_e32 v25, 0x4b800000, v24
	v_cmp_gt_f32_e32 vcc, s66, v24
	s_nop 1
	v_cndmask_b32_e32 v24, v24, v25, vcc
	v_rsq_f32_e32 v26, v24
	v_mul_f32_e32 v24, 0xbfb8aa3b, v20
	v_mul_f32_e32 v25, 0xbfb8aa3b, v21
	v_exp_f32_e32 v24, v24
	v_exp_f32_e32 v25, v25
	v_mul_f32_e32 v27, 0x45800000, v26
	v_cndmask_b32_e32 v26, v26, v27, vcc
	v_add_f32_e32 v24, 1.0, v24
	v_add_f32_e32 v25, 1.0, v25
	v_rcp_f32_e32 v24, v24
	v_rcp_f32_e32 v25, v25
	v_pk_mul_f32 v[16:17], v[26:27], v[16:17] op_sel_hi:[0,1]
	v_pk_mul_f32 v[16:17], v[0:1], v[16:17]
	v_pk_mul_f32 v[12:13], v[26:27], v[12:13] op_sel_hi:[0,1]
	v_pk_mul_f32 v[20:21], v[24:25], v[20:21]
	v_mul_f32_e32 v24, 0xbfb8aa3b, v8
	v_pk_mul_f32 v[16:17], v[16:17], v[20:21]
	v_mul_f32_e32 v20, 0xbfb8aa3b, v9
	v_exp_f32_e32 v24, v24
	v_exp_f32_e32 v21, v20
	v_pk_mul_f32 v[12:13], v[2:3], v[12:13]
	v_pk_mul_f32 v[18:19], v[26:27], v[18:19] op_sel_hi:[0,1]
	v_add_f32_e32 v20, 1.0, v24
	v_add_f32_e32 v21, 1.0, v21
	v_rcp_f32_e32 v20, v20
	v_rcp_f32_e32 v21, v21
	v_mul_f32_e32 v24, 0xbfb8aa3b, v22
	v_exp_f32_e32 v24, v24
	v_pk_mul_f32 v[18:19], v[4:5], v[18:19]
	v_pk_mul_f32 v[8:9], v[20:21], v[8:9]
	v_mul_f32_e32 v20, 0xbfb8aa3b, v10
	v_pk_mul_f32 v[12:13], v[12:13], v[8:9]
	v_mul_f32_e32 v9, 0xbfb8aa3b, v23
	v_exp_f32_e32 v9, v9
	v_mul_f32_e32 v21, 0xbfb8aa3b, v11
	v_exp_f32_e32 v20, v20
	v_exp_f32_e32 v21, v21
	v_add_f32_e32 v8, 1.0, v24
	v_add_f32_e32 v9, 1.0, v9
	v_rcp_f32_e32 v8, v8
	v_rcp_f32_e32 v9, v9
	v_add_f32_e32 v20, 1.0, v20
	v_add_f32_e32 v21, 1.0, v21
	v_rcp_f32_e32 v20, v20
	v_rcp_f32_e32 v21, v21
	v_pk_mul_f32 v[8:9], v[8:9], v[22:23]
	v_pk_mul_f32 v[10:11], v[20:21], v[10:11]
	v_pk_mul_f32 v[18:19], v[18:19], v[8:9]
	v_pk_mul_f32 v[8:9], v[26:27], v[14:15] op_sel_hi:[0,1]
	v_ashrrev_i32_e32 v20, 2, v44
	v_pk_mul_f32 v[8:9], v[6:7], v[8:9]
	v_ashrrev_i32_e32 v21, 31, v20
	v_pk_mul_f32 v[14:15], v[8:9], v[10:11]
	v_cvt_pk_bf16_f32 v9, v12, v13
	v_lshlrev_b64 v[12:13], 11, v[20:21]
	v_cvt_pk_bf16_f32 v8, v16, v17
	v_cvt_pk_bf16_f32 v10, v18, v19
	v_cvt_pk_bf16_f32 v11, v14, v15
	v_lshl_add_u64 v[12:13], v[36:37], 0, v[12:13]
	global_store_dwordx4 v[12:13], v[8:11], off
	s_branch .LBB0_795
